# W_down conversion split 1/8 in P6, 7/8 in the gate/up GEMM tail (was 1/4, 3/4); on v48
# baseline (speedup 1.0000x reference)
; #define LAS __attribute__((address_space(3)))
; template <bool NT> __device__ __forceinline__ void p0_weights(Frame& F, int lo, int NITEMS, int widx, int nworkers) {
;     LAS float* scr = (LAS float*)(F.lds + RING_OFF + F.wave * 16640);
;     const int gw = widx * NWAVES + F.wave, NGW = nworkers * NWAVES;
;     const int g4 = (F.lane & 15) * 4;
;     f32x4 va[16], vb[16];
;     int it = lo + gw; if (it >= NITEMS) return;
;     TrItem ta = p0_item(F, it, g4), tb = ta;
.LBB0_1208:
	s_add_u32 s90, s82, 0x20c00000
	s_addc_u32 s91, s83, 0
	s_cmp_lt_i32 s86, 7
	s_cselect_b64 s[0:1], -1, 0
	s_cmp_gt_i32 s87, 6
	s_cselect_b64 s[4:5], -1, 0
	s_and_b64 s[0:1], s[0:1], s[4:5]
	s_andn2_b64 vcc, exec, s[0:1]
	s_cbranch_vccnz .LBB0_1681
	v_mov_b32_e32 v135, v0
	s_nop 0
	v_readfirstlane_b32 s0, v135
	s_ashr_i32 s18, s0, 6
	s_cmp_gt_u32 s95, 31
	v_and_b32_e32 v1, 63, v135
	s_cbranch_scc0 .LBB0_1218
	s_cmpk_lt_i32 s3, 0x78
	s_cbranch_scc1 .LBB0_1219
	s_add_i32 s0, s95, 0xffffffa0
	s_cmp_gt_u32 s0, 23
	s_cbranch_scc0 .LBB0_1220
	s_cmpk_gt_i32 s95, 0x5f
	v_mov_b32_e32 v2, v135
	s_cbranch_scc1 .LBB0_1419
	s_lshl_b32 s0, s95, 3
	s_add_i32 s0, s0, s18
	s_add_i32 s27, s0, 0x3740
	s_cmp_gt_i32 s27, 0xa39f
	s_cbranch_scc1 .LBB0_1418
	s_add_u32 s2, s82, 0x2000000
	s_addc_u32 s16, s83, 0
	s_add_u32 s17, s82, 0x9800000
	s_addc_u32 s19, s83, 0
	s_add_u32 s20, s82, 0xbc00000
	s_addc_u32 s21, s83, 0
	s_add_u32 s0, s82, 0x17000000
	v_lshlrev_b32_e32 v2, 2, v1
	s_addc_u32 s1, s83, 0
	s_cmpk_gt_i32 s27, 0x383f
	v_and_b32_e32 v134, 60, v2
	s_cbranch_scc0 .LBB0_1222
	s_cmpk_gt_u32 s27, 0x483f
	s_cbranch_scc0 .LBB0_1223
	s_cmpk_gt_u32 s27, 0x9e3f
	s_cbranch_scc0 .LBB0_1224
	s_add_i32 s4, s27, 0x61c0
	s_and_b32 s5, s4, 0xffff
	s_mul_i32 s5, s5, 0xbe83
	s_lshr_b32 s6, s5, 23
	s_mul_i32 s5, s6, 0xac
	s_sub_i32 s4, s4, s5
	s_lshl_b32 s4, s4, 6
	s_and_b32 s7, s4, 0xffc0
	s_lshl_b32 s4, s7, 14
	s_add_u32 s4, s78, s4
	s_addc_u32 s5, s79, 0
	s_lshl_b32 s8, s6, 8
	s_add_u32 s4, s4, s8
	s_addc_u32 s5, s5, 0
	v_lshlrev_b32_e32 v2, 2, v134
	s_waitcnt lgkmcnt(0)
	v_mov_b32_e32 v3, 0
	s_mul_i32 s6, s6, 0x158000
	v_lshl_add_u64 v[2:3], s[4:5], 0, v[2:3]
	s_add_u32 s4, s0, s6
	s_addc_u32 s5, s1, 0
	s_lshl_b32 s6, s7, 1
	s_add_u32 s6, s4, s6
	s_addc_u32 s7, s5, 0
	s_mov_b64 s[4:5], 0
	s_branch .LBB0_1225

; template <bool NT> __device__ __forceinline__ void p0_weights(Frame& F, int lo, int NITEMS, int widx, int nworkers) {
;     ...
;     for (;;) {
;         const bool hb = it + NGW < NITEMS;
;         if (hb) { tb = p0_item(F, it + NGW, g4); tr_load<NT>(vb, tb, F.lane); }
;         tr_store<NT>(va, ta, scr, F.lane);
;         if (!hb) break;
.LBB0_1290:
	s_cmp_lt_i32 s27, 0xa1a0
	s_cselect_b64 s[6:7], -1, 0
	s_cmp_gt_i32 s27, 0xa19f
	s_cbranch_scc1 .LBB0_1350
	s_add_i32 s29, s27, 0x200
	s_cmpk_gt_i32 s27, 0x363f
	s_cbranch_scc0 .LBB0_1296
	s_cmpk_gt_u32 s29, 0x483f
	s_cbranch_scc0 .LBB0_1297
	s_cmpk_gt_u32 s29, 0x9e3f
	s_cbranch_scc0 .LBB0_1358
	s_add_i32 s4, s29, 0x61c0
	s_and_b32 s8, s4, 0xffff
	s_mul_i32 s8, s8, 0xbe83
	s_lshr_b32 s8, s8, 23
	s_mul_i32 s9, s8, 0xac
	s_sub_i32 s4, s4, s9
	s_lshl_b32 s4, s4, 6
	s_and_b32 s4, s4, 0xffc0
	s_lshl_b32 s9, s4, 14
	s_add_u32 s9, s78, s9
	s_addc_u32 s10, s79, 0
	s_lshl_b32 s11, s8, 6
	s_lshl_b32 s8, s8, 8
	s_add_u32 s8, s9, s8
	s_addc_u32 s9, s10, 0
	v_lshlrev_b32_e32 v4, 2, v134
	v_mov_b32_e32 v5, v2
	v_mov_b64_e32 v[54:55], s[0:1]
	v_lshl_add_u64 v[4:5], s[8:9], 0, v[4:5]
	v_mad_u64_u32 v[54:55], s[8:9], s11, v170, v[54:55]
	s_lshl_b32 s4, s4, 1
	v_lshl_add_u64 v[156:157], v[54:55], 0, s[4:5]
	s_cbranch_execz .LBB0_1359
	s_mov_b64 s[8:9], 0x1000
	s_movk_i32 s28, 0x2b00
	s_cbranch_execz .LBB0_1298
	s_branch .LBB0_1299

; #define GAS __attribute__((address_space(1)))
; #define LAS __attribute__((address_space(3)))
; #define LDS_WAIT() asm volatile("s_waitcnt lgkmcnt(0)" ::: "memory")
; __device__ __forceinline__ unsigned pk2(float lo, float hi) { pkf32x2 v = {lo, hi}; pkbf16x2 b = __builtin_convertvector(v, pkbf16x2); return __builtin_bit_cast(unsigned, b); }
; template <bool NT> __device__ __forceinline__ void tr_store(const f32x4 (&v)[16], const TrItem& it, LAS float* scr, int lane) {
;     const int kq = lane >> 4, g = lane & 15;
; #pragma unroll
;     for (int i = 0; i < 16; ++i) { LAS float* d = scr + (4 * i + kq) * 65 + 4 * g; d[0] = v[i].x; d[1] = v[i].y; d[2] = v[i].z; d[3] = v[i].w; }
;     LDS_WAIT(); asm volatile("" ::: "memory");
;     const int c = lane >> 3, rr = lane & 7;
; #pragma unroll
;     for (int j = 0; j < 8; ++j) { const int n = 8 * j + rr; const LAS float* s = scr + (8 * c) * 65 + n;
;         v4u o; o.x = pk2(s[0 * 65], s[1 * 65]); o.y = pk2(s[2 * 65], s[3 * 65]); o.z = pk2(s[4 * 65], s[5 * 65]); o.w = pk2(s[6 * 65], s[7 * 65]);
;         GAS v4u* q = (GAS v4u*)(it.dst + (size_t)n * it.K + 8 * c); if (NT) __builtin_nontemporal_store(o, q); else *q = o; }
;     LDS_WAIT(); asm volatile("" ::: "memory");
; }
.LBB0_1350:
	v_add_u32_e32 v174, 0x410, v172
	v_add_u32_e32 v175, 0x418, v172
	v_add_u32_e32 v176, 0x820, v172
	v_add_u32_e32 v177, 0x828, v172
	v_add_u32_e32 v178, 0xc30, v172
	v_add_u32_e32 v179, 0xc38, v172
	v_add_u32_e32 v180, 0x1040, v172
	v_add_u32_e32 v181, 0x1048, v172
	v_add_u32_e32 v182, 0x1450, v172
	v_add_u32_e32 v183, 0x1458, v172
	v_add_u32_e32 v184, 0x1860, v172
	v_add_u32_e32 v185, 0x1868, v172
	v_add_u32_e32 v186, 0x1c70, v172
	v_add_u32_e32 v187, 0x1c78, v172
	v_add_u32_e32 v188, 0x2080, v172
	v_add_u32_e32 v189, 0x2088, v172
	v_add_u32_e32 v190, 0x2490, v172
	v_add_u32_e32 v191, 0x2498, v172
	v_add_u32_e32 v192, 0x28a0, v172
	v_add_u32_e32 v193, 0x28a8, v172
	v_add_u32_e32 v194, 0x2cb0, v172
	v_add_u32_e32 v195, 0x2cb8, v172
	v_add_u32_e32 v196, 0x30c0, v172
	v_add_u32_e32 v197, 0x30c8, v172
	v_add_u32_e32 v198, 0x34d0, v172
	v_add_u32_e32 v199, 0x34d8, v172
	v_add_u32_e32 v200, 0x38e0, v172
	v_add_u32_e32 v201, 0x38e8, v172
	v_add_u32_e32 v202, 0x3cf0, v172
	v_add_u32_e32 v203, 0x3cf8, v172
	s_waitcnt vmcnt(0)
	ds_write2_b32 v172, v10, v11 offset1:1
	ds_write2_b32 v172, v12, v13 offset0:2 offset1:3
	ds_write2_b32 v174, v6, v7 offset1:1
	ds_write2_b32 v175, v8, v9 offset1:1
	ds_write2_b32 v176, v14, v15 offset1:1
	ds_write2_b32 v177, v16, v17 offset1:1
	ds_write2_b32 v178, v18, v19 offset1:1
	ds_write2_b32 v179, v20, v21 offset1:1
	ds_write2_b32 v180, v22, v23 offset1:1
	ds_write2_b32 v181, v24, v25 offset1:1
	ds_write2_b32 v182, v26, v27 offset1:1
	ds_write2_b32 v183, v28, v29 offset1:1
	ds_write2_b32 v184, v30, v31 offset1:1
	ds_write2_b32 v185, v32, v33 offset1:1
	ds_write2_b32 v186, v34, v35 offset1:1
	ds_write2_b32 v187, v36, v37 offset1:1
	ds_write2_b32 v188, v38, v39 offset1:1
	ds_write2_b32 v189, v40, v41 offset1:1
	ds_write2_b32 v190, v42, v43 offset1:1
	ds_write2_b32 v191, v44, v45 offset1:1
	ds_write2_b32 v192, v46, v47 offset1:1
	ds_write2_b32 v193, v48, v49 offset1:1
	ds_write2_b32 v194, v50, v51 offset1:1
	ds_write2_b32 v195, v52, v53 offset1:1
	ds_write2_b32 v196, v62, v63 offset1:1
	ds_write2_b32 v197, v64, v65 offset1:1
	ds_write2_b32 v198, v74, v75 offset1:1
	ds_write2_b32 v199, v76, v77 offset1:1
	ds_write2_b32 v200, v86, v87 offset1:1
	ds_write2_b32 v201, v88, v89 offset1:1
	ds_write2_b32 v202, v90, v91 offset1:1
	ds_write2_b32 v203, v92, v93 offset1:1
	s_waitcnt lgkmcnt(0)
	v_add_u32_e32 v173, 0x400, v169
	ds_read2_b32 v[4:5], v169 offset0:65 offset1:73
	ds_read2_b32 v[160:161], v169 offset1:8
	ds_read2_b32 v[208:209], v169 offset0:130 offset1:138
	ds_read2_b32 v[210:211], v169 offset0:195 offset1:203
	ds_read2_b32 v[212:213], v173 offset0:4 offset1:12
	ds_read2_b32 v[214:215], v173 offset0:69 offset1:77
	ds_read2_b32 v[216:217], v173 offset0:134 offset1:142
	ds_read2_b32 v[218:219], v173 offset0:199 offset1:207
	v_lshlrev_b32_e32 v158, 1, v138
	v_mov_b32_e32 v159, v2
	v_lshl_add_u64 v[220:221], v[154:155], 0, v[158:159]
	v_mad_u64_u32 v[222:223], s[8:9], s22, v136, 0
	s_waitcnt lgkmcnt(6)
	v_cvt_pk_bf16_f32 v204, v160, v4
	s_waitcnt lgkmcnt(4)
	v_cvt_pk_bf16_f32 v205, v208, v210
	s_waitcnt lgkmcnt(2)
	v_cvt_pk_bf16_f32 v206, v212, v214
	s_waitcnt lgkmcnt(0)
	v_cvt_pk_bf16_f32 v207, v216, v218
	v_lshl_add_u64 v[222:223], v[222:223], 1, v[220:221]
	global_store_dwordx4 v[222:223], v[204:207], off nt
	s_andn2_b64 vcc, exec, s[6:7]
	s_mov_b64 s[6:7], 0
	v_cvt_pk_bf16_f32 v204, v161, v5
	v_cvt_pk_bf16_f32 v205, v209, v211
	v_cvt_pk_bf16_f32 v206, v213, v215
	v_cvt_pk_bf16_f32 v207, v217, v219
	ds_read2_b32 v[160:161], v169 offset0:16 offset1:24
	ds_read2_b32 v[208:209], v169 offset0:81 offset1:89
	ds_read2_b32 v[210:211], v169 offset0:146 offset1:154
	ds_read2_b32 v[212:213], v169 offset0:211 offset1:219
	ds_read2_b32 v[214:215], v173 offset0:20 offset1:28
	ds_read2_b32 v[216:217], v173 offset0:85 offset1:93
	ds_read2_b32 v[218:219], v173 offset0:150 offset1:158
	ds_read2_b32 v[222:223], v173 offset0:215 offset1:223
	v_mad_u64_u32 v[4:5], s[8:9], s22, v140, 0
	v_lshl_add_u64 v[4:5], v[4:5], 1, v[220:221]
	global_store_dwordx4 v[4:5], v[204:207], off nt
	v_mad_u64_u32 v[4:5], s[8:9], s22, v142, 0
	s_waitcnt lgkmcnt(6)
	v_cvt_pk_bf16_f32 v204, v160, v208
	s_waitcnt lgkmcnt(4)
	v_cvt_pk_bf16_f32 v205, v210, v212
	s_waitcnt lgkmcnt(2)
	v_cvt_pk_bf16_f32 v206, v214, v216
	s_waitcnt lgkmcnt(0)
	v_cvt_pk_bf16_f32 v207, v218, v222
	v_lshl_add_u64 v[4:5], v[4:5], 1, v[220:221]
	global_store_dwordx4 v[4:5], v[204:207], off nt
	v_mad_u64_u32 v[4:5], s[8:9], s22, v144, 0
	s_nop 0
	v_cvt_pk_bf16_f32 v204, v161, v209
	v_cvt_pk_bf16_f32 v205, v211, v213
	v_cvt_pk_bf16_f32 v206, v215, v217
	v_cvt_pk_bf16_f32 v207, v219, v223
	ds_read2_b32 v[160:161], v169 offset0:32 offset1:40
	ds_read2_b32 v[208:209], v169 offset0:97 offset1:105
	ds_read2_b32 v[210:211], v169 offset0:162 offset1:170
	ds_read2_b32 v[212:213], v169 offset0:227 offset1:235
	ds_read2_b32 v[214:215], v173 offset0:36 offset1:44
	ds_read2_b32 v[216:217], v173 offset0:101 offset1:109
	ds_read2_b32 v[218:219], v173 offset0:166 offset1:174
	ds_read2_b32 v[222:223], v173 offset0:231 offset1:239
	v_lshl_add_u64 v[4:5], v[4:5], 1, v[220:221]
	global_store_dwordx4 v[4:5], v[204:207], off nt
	v_mad_u64_u32 v[4:5], s[8:9], s22, v146, 0
	s_waitcnt lgkmcnt(6)
	v_cvt_pk_bf16_f32 v204, v160, v208
	s_waitcnt lgkmcnt(4)
	v_cvt_pk_bf16_f32 v205, v210, v212
	s_waitcnt lgkmcnt(2)
	v_cvt_pk_bf16_f32 v206, v214, v216
	s_waitcnt lgkmcnt(0)
	v_cvt_pk_bf16_f32 v207, v218, v222
	v_lshl_add_u64 v[4:5], v[4:5], 1, v[220:221]
	global_store_dwordx4 v[4:5], v[204:207], off nt
	v_mad_u64_u32 v[4:5], s[8:9], s22, v148, 0
	s_nop 0
	v_cvt_pk_bf16_f32 v204, v161, v209
	v_cvt_pk_bf16_f32 v205, v211, v213
	v_cvt_pk_bf16_f32 v206, v215, v217
	v_cvt_pk_bf16_f32 v207, v219, v223
	ds_read2_b32 v[160:161], v169 offset0:48 offset1:56
	ds_read2_b32 v[208:209], v169 offset0:113 offset1:121
	ds_read2_b32 v[210:211], v169 offset0:178 offset1:186
	ds_read2_b32 v[212:213], v169 offset0:243 offset1:251
	ds_read2_b32 v[214:215], v173 offset0:52 offset1:60
	ds_read2_b32 v[216:217], v173 offset0:117 offset1:125
	ds_read2_b32 v[218:219], v173 offset0:182 offset1:190
	ds_read2_b32 v[222:223], v173 offset0:247 offset1:255
	v_lshl_add_u64 v[4:5], v[4:5], 1, v[220:221]
	global_store_dwordx4 v[4:5], v[204:207], off nt
	v_mad_u64_u32 v[4:5], s[8:9], s22, v150, 0
	s_waitcnt lgkmcnt(6)
	v_cvt_pk_bf16_f32 v204, v160, v208
	s_waitcnt lgkmcnt(4)
	v_cvt_pk_bf16_f32 v205, v210, v212
	s_waitcnt lgkmcnt(2)
	v_cvt_pk_bf16_f32 v206, v214, v216
	s_waitcnt lgkmcnt(0)
	v_cvt_pk_bf16_f32 v207, v218, v222
	v_lshl_add_u64 v[4:5], v[4:5], 1, v[220:221]
	global_store_dwordx4 v[4:5], v[204:207], off nt
	v_mad_u64_u32 v[4:5], s[8:9], s22, v152, 0
	s_nop 0
	v_cvt_pk_bf16_f32 v204, v161, v209
	v_cvt_pk_bf16_f32 v205, v211, v213
	v_cvt_pk_bf16_f32 v206, v215, v217
	v_cvt_pk_bf16_f32 v207, v219, v223
	v_lshl_add_u64 v[4:5], v[4:5], 1, v[220:221]
	global_store_dwordx4 v[4:5], v[204:207], off nt
	s_waitcnt lgkmcnt(0)
	s_cbranch_vccnz .LBB0_1289
; template <bool NT> __device__ __forceinline__ void p0_weights(Frame& F, int lo, int NITEMS, int widx, int nworkers) {
;     ...
;         const bool ha = it + 2 * NGW < NITEMS;
;         if (ha) { ta = p0_item(F, it + 2 * NGW, g4); tr_load<NT>(va, ta, F.lane); }
;         tr_store<NT>(vb, tb, scr, F.lane);
;         if (!ha) break;
	s_cmp_lt_i32 s27, 0x9fa0
	s_cselect_b64 s[6:7], -1, 0
	s_cmp_gt_i32 s27, 0x9f9f
	s_cbranch_scc1 .LBB0_1356
	s_add_i32 s29, s27, 0x400
	s_cmpk_gt_i32 s27, 0x343f
	s_cbranch_scc0 .LBB0_1357
	s_cmpk_gt_u32 s29, 0x483f
	s_cbranch_scc0 .LBB0_1360
	s_cmpk_gt_u32 s29, 0x9e3f
	s_cbranch_scc0 .LBB0_1361
	s_add_i32 s4, s29, 0x61c0
	s_and_b32 s8, s4, 0xffff
	s_mul_i32 s8, s8, 0xbe83
	s_lshr_b32 s8, s8, 23
	s_mul_i32 s9, s8, 0xac
	s_sub_i32 s4, s4, s9
	s_lshl_b32 s4, s4, 6
	s_and_b32 s4, s4, 0xffc0
	s_lshl_b32 s9, s4, 14
	s_add_u32 s9, s78, s9
	s_addc_u32 s10, s79, 0
	s_lshl_b32 s11, s8, 6
	s_lshl_b32 s8, s8, 8
	s_add_u32 s8, s9, s8
	s_addc_u32 s9, s10, 0
	v_lshlrev_b32_e32 v4, 2, v134
	v_mov_b32_e32 v5, v2
	v_lshl_add_u64 v[160:161], s[8:9], 0, v[4:5]
	v_mov_b64_e32 v[4:5], s[0:1]
	v_mad_u64_u32 v[4:5], s[8:9], s11, v170, v[4:5]
	s_lshl_b32 s4, s4, 1
	v_lshl_add_u64 v[154:155], v[4:5], 0, s[4:5]
	s_mov_b64 s[8:9], 0
	s_branch .LBB0_1362

; #define LAS __attribute__((address_space(3)))
; template <bool NT> __device__ __forceinline__ void p0_weights(Frame& F, int lo, int NITEMS, int widx, int nworkers) {
;     LAS float* scr = (LAS float*)(F.lds + RING_OFF + F.wave * 16640);
;     const int gw = widx * NWAVES + F.wave, NGW = nworkers * NWAVES;
;     const int g4 = (F.lane & 15) * 4;
;     f32x4 va[16], vb[16];
;     int it = lo + gw; if (it >= NITEMS) return;
;     TrItem ta = p0_item(F, it, g4), tb = ta;
.LBB0_1896:
	s_abs_i32 s0, s3
	v_cvt_f32_u32_e32 v1, s0
	s_sub_i32 s1, 0, s0
	v_rcp_iflag_f32_e32 v1, v1
	s_nop 0
	v_mul_f32_e32 v1, 0x4f7ffffe, v1
	v_cvt_u32_f32_e32 v1, v1
	s_nop 0
	v_readfirstlane_b32 s2, v1
	s_mul_i32 s1, s1, s2
	s_mul_hi_u32 s1, s2, s1
	s_add_i32 s2, s2, s1
	s_mul_hi_u32 s1, s2, 0xac0
	s_mul_i32 s1, s1, s0
	s_sub_i32 s1, 0xac0, s1
	s_sub_i32 s2, s1, s0
	s_cmp_ge_u32 s1, s0
	s_cselect_b32 s1, s2, s1
	s_sub_i32 s2, s1, s0
	s_cmp_ge_u32 s1, s0
	s_cselect_b32 s12, s2, s1
	s_cmp_lt_i32 s95, s12
	s_cbranch_scc1 .LBB0_2093
	v_mov_b32_e32 v4, v0
	s_nop 0
	v_readfirstlane_b32 s0, v4
	s_ashr_i32 s13, s0, 6
	s_sub_i32 s0, s95, s12
	s_lshl_b32 s0, s0, 3
	s_add_i32 s0, s0, s13
	s_add_i32 s20, s0, 0xa3a0
	s_cmp_gt_i32 s20, 0xc93f
	s_cbranch_scc1 .LBB0_2093
	s_add_u32 s2, s82, 0x2000000
	s_addc_u32 s16, s83, 0
	s_add_u32 s17, s82, 0x9800000
	s_addc_u32 s18, s83, 0
	s_add_u32 s0, s82, 0x17000000
	v_lshlrev_b32_e32 v1, 2, v4
	s_addc_u32 s1, s83, 0
	s_cmpk_gt_i32 s20, 0x383f
	v_and_b32_e32 v134, 60, v1
	s_cbranch_scc0 .LBB0_1902
	s_cmpk_gt_u32 s20, 0x483f
	s_cbranch_scc0 .LBB0_1903
	s_cmpk_gt_u32 s20, 0x9e3f
	s_cbranch_scc0 .LBB0_1904
	s_add_i32 s4, s20, 0x61c0
	s_and_b32 s5, s4, 0xffff
	s_mul_i32 s5, s5, 0xbe83
	s_lshr_b32 s6, s5, 23
	s_mul_i32 s5, s6, 0xac
	s_sub_i32 s4, s4, s5
	s_lshl_b32 s4, s4, 6
	s_and_b32 s7, s4, 0xffc0
	s_lshl_b32 s4, s7, 14
	s_add_u32 s4, s78, s4
	s_addc_u32 s5, s79, 0
	s_lshl_b32 s8, s6, 8
	s_add_u32 s4, s4, s8
	s_addc_u32 s5, s5, 0
	v_lshlrev_b32_e32 v2, 2, v134
	s_waitcnt lgkmcnt(0)
	v_mov_b32_e32 v3, 0
	s_mul_i32 s6, s6, 0x158000
	v_lshl_add_u64 v[2:3], s[4:5], 0, v[2:3]
	s_add_u32 s4, s0, s6
	s_addc_u32 s5, s1, 0
	s_lshl_b32 s6, s7, 1
	s_add_u32 s6, s4, s6
	s_addc_u32 s7, s5, 0
	s_mov_b64 s[4:5], 0
	s_branch .LBB0_1905
